# v20 + DIFF attention steady-state tile loop: ALiBi bias built as one fma + 32 v_fmamk (keys there always precede the query rows, so |t-s| = t-s) instead of 16 pk_add + 32 v_and + 16 pk_fma; f32 math a
# speedup vs baseline: 1.0056x; 1.0040x over previous
.LBB0_324:
	v_cvt_f32_i32_e32 v199, v158
	s_and_b32 s21, s20, 0x4000
	v_add_u32_e32 v149, s21, v231
	v_add_u32_e32 v151, v149, v154
	ds_read_b128 v[160:163], v151 offset:32768
	ds_read_b128 v[164:167], v151 offset:40960
	ds_read_b128 v[168:171], v147
	v_fma_f32 v199, v198, v199, -v146
	v_mov_b32_e32 v68, v199
	v_fmamk_f32 v69, v198, 0xbf800000, v199
	v_fmamk_f32 v70, v198, 0xc0000000, v199
	v_fmamk_f32 v71, v198, 0xc0400000, v199
	v_fmamk_f32 v72, v198, 0xc1000000, v199
	v_fmamk_f32 v73, v198, 0xc1100000, v199
	v_fmamk_f32 v74, v198, 0xc1200000, v199
	v_fmamk_f32 v75, v198, 0xc1300000, v199
	v_fmamk_f32 v76, v198, 0xc1800000, v199
	v_fmamk_f32 v77, v198, 0xc1880000, v199
	v_fmamk_f32 v78, v198, 0xc1900000, v199
	v_fmamk_f32 v79, v198, 0xc1980000, v199
	v_fmamk_f32 v80, v198, 0xc1c00000, v199
	v_fmamk_f32 v81, v198, 0xc1c80000, v199
	v_fmamk_f32 v82, v198, 0xc1d00000, v199
	v_fmamk_f32 v83, v198, 0xc1d80000, v199
	v_fmamk_f32 v116, v198, 0xc2000000, v199
	v_fmamk_f32 v117, v198, 0xc2040000, v199
	v_fmamk_f32 v118, v198, 0xc2080000, v199
	v_fmamk_f32 v119, v198, 0xc20c0000, v199
	v_fmamk_f32 v120, v198, 0xc2200000, v199
	v_fmamk_f32 v121, v198, 0xc2240000, v199
	v_fmamk_f32 v122, v198, 0xc2280000, v199
	v_fmamk_f32 v123, v198, 0xc22c0000, v199
	v_fmamk_f32 v124, v198, 0xc2400000, v199
	v_fmamk_f32 v125, v198, 0xc2440000, v199
	v_fmamk_f32 v126, v198, 0xc2480000, v199
	v_fmamk_f32 v127, v198, 0xc24c0000, v199
	v_fmamk_f32 v128, v198, 0xc2600000, v199
	v_fmamk_f32 v129, v198, 0xc2640000, v199
	v_fmamk_f32 v130, v198, 0xc2680000, v199
	v_fmamk_f32 v131, v198, 0xc26c0000, v199
	v_add_u32_e32 v151, v149, v155
	s_waitcnt lgkmcnt(0)
	v_mfma_f32_32x32x16_bf16 v[68:83], v[160:163], v[168:171], v[68:83]
	v_mfma_f32_32x32x16_bf16 v[116:131], v[164:167], v[168:171], v[116:131]
	ds_read_b128 v[160:163], v151 offset:32768
	ds_read_b128 v[164:167], v151 offset:40960
	ds_read_b128 v[168:171], v147 offset:1024
	v_add_u32_e32 v151, v149, v156
	v_add_u32_e32 v149, v149, v157
	s_waitcnt lgkmcnt(0)
	v_mfma_f32_32x32x16_bf16 v[68:83], v[160:163], v[168:171], v[68:83]
	v_mfma_f32_32x32x16_bf16 v[116:131], v[164:167], v[168:171], v[116:131]
	ds_read_b128 v[160:163], v151 offset:32768
	ds_read_b128 v[164:167], v151 offset:40960
	ds_read_b128 v[168:171], v147 offset:2048
	s_waitcnt lgkmcnt(0)
	v_mfma_f32_32x32x16_bf16 v[68:83], v[160:163], v[168:171], v[68:83]
	v_mfma_f32_32x32x16_bf16 v[116:131], v[164:167], v[168:171], v[116:131]
	ds_read_b128 v[160:163], v149 offset:32768
	ds_read_b128 v[164:167], v149 offset:40960
	ds_read_b128 v[168:171], v147 offset:3072
	s_waitcnt lgkmcnt(0)
	v_mfma_f32_32x32x16_bf16 v[68:83], v[160:163], v[168:171], v[68:83]
	v_mfma_f32_32x32x16_bf16 v[116:131], v[164:167], v[168:171], v[116:131]
	s_nop 10
	v_max_f32_e32 v149, v69, v69
	v_max_f32_e32 v151, v68, v68
	v_max_f32_e32 v149, v151, v149
	v_max3_f32 v149, v149, v70, v71
	v_max3_f32 v149, v149, v72, v73
	v_max3_f32 v149, v149, v74, v75
	v_max3_f32 v149, v149, v76, v77
	v_max3_f32 v149, v149, v78, v79
	v_max3_f32 v149, v149, v80, v81
	v_max3_f32 v149, v149, v82, v83
	v_max3_f32 v149, v149, v116, v117
	v_max3_f32 v149, v149, v118, v119
	v_max3_f32 v149, v149, v120, v121
	v_max3_f32 v149, v149, v122, v123
	v_max3_f32 v149, v149, v124, v125
	v_max3_f32 v149, v149, v126, v127
	v_max3_f32 v149, v149, v128, v129
	v_max3_f32 v149, v149, v130, v131
	v_mov_b32_e32 v151, v149
	s_nop 1
	v_permlane32_swap_b32_e32 v149, v151
	v_max3_f32 v152, v149, v151, 0
	v_exp_f32_e64 v149, -v152
	v_cmp_neq_f32_e32 vcc, 0, v152
	s_cbranch_vccz .LBB0_328
	s_and_saveexec_b64 s[22:23], s[40:41]
	ds_write_b32 v232, v149
	s_or_b64 exec, exec, s[22:23]
	s_waitcnt lgkmcnt(0)
	v_add_u32_e32 v151, s33, v229
	ds_read_b128 v[160:163], v151 offset:64
	ds_read_b128 v[164:167], v151 offset:96
	ds_read_b128 v[168:171], v151
	ds_read_b128 v[172:175], v151 offset:32
	v_pk_add_f32 v[68:69], v[68:69], v[152:153] op_sel_hi:[1,0] neg_lo:[0,1] neg_hi:[0,1]
	v_pk_add_f32 v[116:117], v[116:117], v[152:153] op_sel_hi:[1,0] neg_lo:[0,1] neg_hi:[0,1]
	v_pk_add_f32 v[70:71], v[70:71], v[152:153] op_sel_hi:[1,0] neg_lo:[0,1] neg_hi:[0,1]
	v_pk_add_f32 v[118:119], v[118:119], v[152:153] op_sel_hi:[1,0] neg_lo:[0,1] neg_hi:[0,1]
	v_pk_add_f32 v[72:73], v[72:73], v[152:153] op_sel_hi:[1,0] neg_lo:[0,1] neg_hi:[0,1]
	v_pk_add_f32 v[120:121], v[120:121], v[152:153] op_sel_hi:[1,0] neg_lo:[0,1] neg_hi:[0,1]
	v_pk_add_f32 v[74:75], v[74:75], v[152:153] op_sel_hi:[1,0] neg_lo:[0,1] neg_hi:[0,1]
	v_pk_add_f32 v[122:123], v[122:123], v[152:153] op_sel_hi:[1,0] neg_lo:[0,1] neg_hi:[0,1]
	v_pk_add_f32 v[76:77], v[76:77], v[152:153] op_sel_hi:[1,0] neg_lo:[0,1] neg_hi:[0,1]
	v_pk_add_f32 v[124:125], v[124:125], v[152:153] op_sel_hi:[1,0] neg_lo:[0,1] neg_hi:[0,1]
	v_pk_add_f32 v[78:79], v[78:79], v[152:153] op_sel_hi:[1,0] neg_lo:[0,1] neg_hi:[0,1]
	v_pk_add_f32 v[126:127], v[126:127], v[152:153] op_sel_hi:[1,0] neg_lo:[0,1] neg_hi:[0,1]
	v_pk_add_f32 v[80:81], v[80:81], v[152:153] op_sel_hi:[1,0] neg_lo:[0,1] neg_hi:[0,1]
	v_pk_add_f32 v[128:129], v[128:129], v[152:153] op_sel_hi:[1,0] neg_lo:[0,1] neg_hi:[0,1]
	v_pk_add_f32 v[82:83], v[82:83], v[152:153] op_sel_hi:[1,0] neg_lo:[0,1] neg_hi:[0,1]
	v_pk_add_f32 v[130:131], v[130:131], v[152:153] op_sel_hi:[1,0] neg_lo:[0,1] neg_hi:[0,1]
	s_waitcnt lgkmcnt(2)
	v_pk_mul_f32 v[64:65], v[64:65], v[164:165]
	v_pk_mul_f32 v[60:61], v[60:61], v[160:161]
	s_waitcnt lgkmcnt(0)
	v_pk_mul_f32 v[56:57], v[56:57], v[172:173]
	v_pk_mul_f32 v[66:67], v[66:67], v[166:167]
	v_pk_mul_f32 v[62:63], v[62:63], v[162:163]
	v_pk_mul_f32 v[58:59], v[58:59], v[174:175]
	v_pk_mul_f32 v[54:55], v[54:55], v[170:171]
	v_pk_mul_f32 v[52:53], v[52:53], v[168:169]
	v_pk_mul_f32 v[96:97], v[96:97], v[164:165]
	v_pk_mul_f32 v[92:93], v[92:93], v[160:161]
	v_pk_mul_f32 v[88:89], v[88:89], v[172:173]
	v_pk_mul_f32 v[98:99], v[98:99], v[166:167]
	v_pk_mul_f32 v[94:95], v[94:95], v[162:163]
	v_pk_mul_f32 v[90:91], v[90:91], v[174:175]
	v_pk_mul_f32 v[86:87], v[86:87], v[170:171]
	v_pk_mul_f32 v[84:85], v[84:85], v[168:169]
	v_pk_mul_f32 v[112:113], v[112:113], v[164:165]
	v_pk_mul_f32 v[108:109], v[108:109], v[160:161]
	v_pk_mul_f32 v[104:105], v[104:105], v[172:173]
	v_pk_mul_f32 v[114:115], v[114:115], v[166:167]
	v_pk_mul_f32 v[110:111], v[110:111], v[162:163]
	v_pk_mul_f32 v[106:107], v[106:107], v[174:175]
	v_pk_mul_f32 v[102:103], v[102:103], v[170:171]
	v_pk_mul_f32 v[100:101], v[100:101], v[168:169]
	v_pk_mul_f32 v[48:49], v[48:49], v[164:165]
	v_pk_mul_f32 v[44:45], v[44:45], v[160:161]
	v_pk_mul_f32 v[40:41], v[40:41], v[172:173]
	v_pk_mul_f32 v[50:51], v[50:51], v[166:167]
	v_pk_mul_f32 v[46:47], v[46:47], v[162:163]
	v_pk_mul_f32 v[42:43], v[42:43], v[174:175]
	v_pk_mul_f32 v[38:39], v[38:39], v[170:171]
	v_pk_mul_f32 v[36:37], v[36:37], v[168:169]
